# final phase rows remapped XCD-locally, light barrier before it (census-guarded)
# baseline (speedup 1.0000x reference)
.Lxb_have_census:
	v_readlane_b32 s28, v253, 61
	v_readlane_b32 s29, v253, 62
	v_readlane_b32 s38, v254, 1
	v_readlane_b32 s39, v254, 2
	v_mov_b32_e32 v3, 1
	s_mul_i32 s2, s2, s37
	s_mul_i32 s3, s3, s37
	s_nop 4
	global_atomic_add v3, v201, v3, s[28:29] sc0
	buffer_inv sc1
	s_waitcnt vmcnt(0)
	v_readfirstlane_b32 s28, v3
	s_nop 3
	s_add_u32 s28, s28, 1
	s_cmp_eq_u32 s28, s2
	s_cbranch_scc0 .Lxb_poll
	s_cmp_eq_u32 s74, 14
	s_cbranch_scc1 .Lxb_maybe_light
	s_cmp_eq_u32 s74, 7
	s_cbranch_scc1 .Lxb_maybe_light
	s_cmp_eq_u32 s74, 8
	s_cbranch_scc1 .Lxb_maybe_light
	s_cmp_eq_u32 s74, 6
	s_cbranch_scc1 .Lxb_maybe_light
	s_cmp_eq_u32 s74, 12
	s_cbranch_scc1 .Lxb_maybe_light
	s_cmp_eq_u32 s74, 13
	s_cbranch_scc1 .Lxb_maybe_light
	s_branch .Lxb_flush

.LBB0_74:
	v_readlane_b32 s30, v253, 0
	v_lshrrev_b32_e32 v0, 8, v228
	s_lshl_b32 s57, s30, 1
	v_readfirstlane_b32 s90, v0
	s_add_i32 s0, s90, s57
	v_writelane_b32 v255, s0, 34
	s_mov_b64 s[36:37], -1
	s_mov_b64 s[0:1], 0
	s_cmp_lt_i32 s74, 1
	s_mov_b64 s[2:3], 0
	s_cbranch_scc1 .LBB0_107
	s_cmp_gt_i32 s74, 13
	s_cbranch_scc0 .LBB0_82
	s_cmp_eq_u32 s74, 14
	s_mov_b64 s[2:3], -1
	s_cbranch_scc0 .LBB0_81
	v_readlane_b32 s2, v255, 34
	v_mov_b32_e32 v0, v229
	s_cmpk_gt_i32 s2, 0x7ff
	s_cbranch_scc1 .LBB0_80
	v_ashrrev_i32_e32 v6, 6, v0
	v_lshlrev_b32_e32 v0, 4, v0
	v_readlane_b32 s36, v253, 3
	v_and_b32_e32 v200, 0x3f0, v0
	v_readlane_b32 s37, v253, 4
	v_readlane_b32 s38, v253, 5
	v_readlane_b32 s39, v253, 6
	v_readlane_b32 s40, v253, 7
	v_readlane_b32 s41, v253, 8
	v_readlane_b32 s42, v253, 9
	v_readlane_b32 s43, v253, 10
	v_readlane_b32 s44, v253, 11
	v_readlane_b32 s45, v253, 12
	v_readlane_b32 s46, v253, 13
	v_readlane_b32 s47, v253, 14
	v_readlane_b32 s48, v253, 15
	v_readlane_b32 s49, v253, 16
	v_readlane_b32 s50, v253, 17
	v_readlane_b32 s51, v253, 18
	s_lshl_b32 s2, s30, 3
	s_lshl_b32 s3, s90, 2
	s_waitcnt lgkmcnt(0)
	v_lshl_add_u64 v[0:1], s[50:51], 0, v[200:201]
	v_readlane_b32 s36, v254, 57
	v_readlane_b32 s37, v254, 58
	s_add_i32 s3, s3, s2
	v_lshl_add_u64 v[2:3], s[18:19], 0, v[200:201]
	v_lshl_add_u64 v[4:5], s[36:37], 0, v[200:201]
	v_mov_b32_e32 v7, v6
	v_add_u32_e32 v6, s3, v6
	v_readlane_b32 s3, v255, 18
	v_readlane_b32 s2, v255, 34
	ds_read_b32 v8, v208 offset:8
	s_waitcnt lgkmcnt(0)
	v_readfirstlane_b32 s36, v8
	s_nop 3
	s_cmp_eq_u32 s36, 1
	s_cbranch_scc0 .Lfin_nomap
	s_cmpk_eq_i32 s68, 0x100
	s_cbranch_scc0 .Lfin_nomap
	s_and_b32 s36, s30, 7
	s_lshl_b32 s36, s36, 10
	s_lshr_b32 s37, s30, 3
	s_lshl_b32 s37, s37, 3
	s_add_i32 s36, s36, s37
	s_lshl_b32 s37, s90, 2
	s_add_i32 s36, s36, s37
	v_add_u32_e32 v6, s36, v7
	s_movk_i32 s3, 0x100
.Lfin_nomap:
	v_readlane_b32 s38, v254, 59
	v_readlane_b32 s39, v254, 60
	v_readlane_b32 s40, v254, 61
	v_readlane_b32 s41, v254, 62
	v_readlane_b32 s42, v254, 63
	v_readlane_b32 s43, v255, 0
	v_readlane_b32 s44, v255, 1
	v_readlane_b32 s45, v255, 2
	v_readlane_b32 s46, v255, 3
	v_readlane_b32 s47, v255, 4
	v_readlane_b32 s48, v255, 5
	v_readlane_b32 s49, v255, 6
	v_readlane_b32 s50, v255, 7
	v_readlane_b32 s51, v255, 8
